# P5 chunk-carry prefix: up to 24 panels per round trip instead of 8 (+ serial remainder loop)
# baseline (speedup 1.0000x reference)
; DEV void p5_pre(const Params& P, int p) {
;     ...
;   __syncthreads();
;   {
;     const int ch = 2 * tid;
;     float Ha = 0.f, Hb = 0.f;
; #pragma unroll 8
;     for (int pp = pfirst; pp < p; ++pp) {
;       const f32x2_t a2 = *(const f32x2_t*)(aprod + pp * DM + ch), h2 = *(const f32x2_t*)(hend + pp * DM + ch);
;       Ha = a2[0] * Ha + h2[0]; Hb = a2[1] * Hb + h2[1];
;     }
.LBB0_697:
	s_mov_b64 s[20:21], s[80:81]
	s_mov_b64 s[80:81], s[82:83]
	v_mov_b32_e32 v0, v176
	s_and_b32 s5, s84, 0xffffff80
	v_lshlrev_b32_e32 v0, 1, v0
	s_cmp_lg_u32 s5, s84
	v_ashrrev_i32_e32 v1, 31, v0
	s_mov_b64 s[0:1], -1
	s_barrier
	s_cbranch_scc0 .LBB0_706
	s_sub_u32 s6, s84, s5
	s_lshl_b32 s7, s5, 12
	s_add_u32 s8, s80, 0x200000
	s_addc_u32 s9, s81, 0
	s_add_u32 s8, s8, s7
	s_addc_u32 s9, s9, 0
	v_lshlrev_b32_e32 v2, 2, v0
	v_add_u32_e32 v3, 0x100000, v2
	v_mov_b32_e32 v6, 0
	v_mov_b32_e32 v7, 0
.Lpfx_batch:
	s_cmp_le_u32 s6, 0
	s_cbranch_scc1 .Lpfx_wait
	global_load_dwordx2 v[8:9], v2, s[8:9]
	global_load_dwordx2 v[10:11], v3, s[8:9]
	s_add_u32 s8, s8, 0x1000
	s_addc_u32 s9, s9, 0
	s_cmp_le_u32 s6, 1
	s_cbranch_scc1 .Lpfx_wait
	global_load_dwordx2 v[12:13], v2, s[8:9]
	global_load_dwordx2 v[14:15], v3, s[8:9]
	s_add_u32 s8, s8, 0x1000
	s_addc_u32 s9, s9, 0
	s_cmp_le_u32 s6, 2
	s_cbranch_scc1 .Lpfx_wait
	global_load_dwordx2 v[16:17], v2, s[8:9]
	global_load_dwordx2 v[18:19], v3, s[8:9]
	s_add_u32 s8, s8, 0x1000
	s_addc_u32 s9, s9, 0
	s_cmp_le_u32 s6, 3
	s_cbranch_scc1 .Lpfx_wait
	global_load_dwordx2 v[20:21], v2, s[8:9]
	global_load_dwordx2 v[22:23], v3, s[8:9]
	s_add_u32 s8, s8, 0x1000
	s_addc_u32 s9, s9, 0
	s_cmp_le_u32 s6, 4
	s_cbranch_scc1 .Lpfx_wait
	global_load_dwordx2 v[24:25], v2, s[8:9]
	global_load_dwordx2 v[26:27], v3, s[8:9]
	s_add_u32 s8, s8, 0x1000
	s_addc_u32 s9, s9, 0
	s_cmp_le_u32 s6, 5
	s_cbranch_scc1 .Lpfx_wait
	global_load_dwordx2 v[28:29], v2, s[8:9]
	global_load_dwordx2 v[30:31], v3, s[8:9]
	s_add_u32 s8, s8, 0x1000
	s_addc_u32 s9, s9, 0
	s_cmp_le_u32 s6, 6
	s_cbranch_scc1 .Lpfx_wait
	global_load_dwordx2 v[32:33], v2, s[8:9]
	global_load_dwordx2 v[34:35], v3, s[8:9]
	s_add_u32 s8, s8, 0x1000
	s_addc_u32 s9, s9, 0
	s_cmp_le_u32 s6, 7
	s_cbranch_scc1 .Lpfx_wait
	global_load_dwordx2 v[36:37], v2, s[8:9]
	global_load_dwordx2 v[38:39], v3, s[8:9]
	s_add_u32 s8, s8, 0x1000
	s_addc_u32 s9, s9, 0
	s_cmp_le_u32 s6, 8
	s_cbranch_scc1 .Lpfx_wait
	global_load_dwordx2 v[40:41], v2, s[8:9]
	global_load_dwordx2 v[42:43], v3, s[8:9]
	s_add_u32 s8, s8, 0x1000
	s_addc_u32 s9, s9, 0
	s_cmp_le_u32 s6, 9
	s_cbranch_scc1 .Lpfx_wait
	global_load_dwordx2 v[44:45], v2, s[8:9]
	global_load_dwordx2 v[46:47], v3, s[8:9]
	s_add_u32 s8, s8, 0x1000
	s_addc_u32 s9, s9, 0
	s_cmp_le_u32 s6, 10
	s_cbranch_scc1 .Lpfx_wait
	global_load_dwordx2 v[48:49], v2, s[8:9]
	global_load_dwordx2 v[50:51], v3, s[8:9]
	s_add_u32 s8, s8, 0x1000
	s_addc_u32 s9, s9, 0
	s_cmp_le_u32 s6, 11
	s_cbranch_scc1 .Lpfx_wait
	global_load_dwordx2 v[52:53], v2, s[8:9]
	global_load_dwordx2 v[54:55], v3, s[8:9]
	s_add_u32 s8, s8, 0x1000
	s_addc_u32 s9, s9, 0
	s_cmp_le_u32 s6, 12
	s_cbranch_scc1 .Lpfx_wait
	global_load_dwordx2 v[56:57], v2, s[8:9]
	global_load_dwordx2 v[58:59], v3, s[8:9]
	s_add_u32 s8, s8, 0x1000
	s_addc_u32 s9, s9, 0
	s_cmp_le_u32 s6, 13
	s_cbranch_scc1 .Lpfx_wait
	global_load_dwordx2 v[60:61], v2, s[8:9]
	global_load_dwordx2 v[62:63], v3, s[8:9]
	s_add_u32 s8, s8, 0x1000
	s_addc_u32 s9, s9, 0
	s_cmp_le_u32 s6, 14
	s_cbranch_scc1 .Lpfx_wait
	global_load_dwordx2 v[64:65], v2, s[8:9]
	global_load_dwordx2 v[66:67], v3, s[8:9]
	s_add_u32 s8, s8, 0x1000
	s_addc_u32 s9, s9, 0
	s_cmp_le_u32 s6, 15
	s_cbranch_scc1 .Lpfx_wait
	global_load_dwordx2 v[68:69], v2, s[8:9]
	global_load_dwordx2 v[70:71], v3, s[8:9]
	s_add_u32 s8, s8, 0x1000
	s_addc_u32 s9, s9, 0
	s_cmp_le_u32 s6, 16
	s_cbranch_scc1 .Lpfx_wait
	global_load_dwordx2 v[72:73], v2, s[8:9]
	global_load_dwordx2 v[74:75], v3, s[8:9]
	s_add_u32 s8, s8, 0x1000
	s_addc_u32 s9, s9, 0
	s_cmp_le_u32 s6, 17
	s_cbranch_scc1 .Lpfx_wait
	global_load_dwordx2 v[76:77], v2, s[8:9]
	global_load_dwordx2 v[78:79], v3, s[8:9]
	s_add_u32 s8, s8, 0x1000
	s_addc_u32 s9, s9, 0
	s_cmp_le_u32 s6, 18
	s_cbranch_scc1 .Lpfx_wait
	global_load_dwordx2 v[80:81], v2, s[8:9]
	global_load_dwordx2 v[82:83], v3, s[8:9]
	s_add_u32 s8, s8, 0x1000
	s_addc_u32 s9, s9, 0
	s_cmp_le_u32 s6, 19
	s_cbranch_scc1 .Lpfx_wait
	global_load_dwordx2 v[84:85], v2, s[8:9]
	global_load_dwordx2 v[86:87], v3, s[8:9]
	s_add_u32 s8, s8, 0x1000
	s_addc_u32 s9, s9, 0
	s_cmp_le_u32 s6, 20
	s_cbranch_scc1 .Lpfx_wait
	global_load_dwordx2 v[88:89], v2, s[8:9]
	global_load_dwordx2 v[90:91], v3, s[8:9]
	s_add_u32 s8, s8, 0x1000
	s_addc_u32 s9, s9, 0
	s_cmp_le_u32 s6, 21
	s_cbranch_scc1 .Lpfx_wait
	global_load_dwordx2 v[92:93], v2, s[8:9]
	global_load_dwordx2 v[94:95], v3, s[8:9]
	s_add_u32 s8, s8, 0x1000
	s_addc_u32 s9, s9, 0
	s_cmp_le_u32 s6, 22
	s_cbranch_scc1 .Lpfx_wait
	global_load_dwordx2 v[96:97], v2, s[8:9]
	global_load_dwordx2 v[98:99], v3, s[8:9]
	s_add_u32 s8, s8, 0x1000
	s_addc_u32 s9, s9, 0
	s_cmp_le_u32 s6, 23
	s_cbranch_scc1 .Lpfx_wait
	global_load_dwordx2 v[100:101], v2, s[8:9]
	global_load_dwordx2 v[102:103], v3, s[8:9]
	s_add_u32 s8, s8, 0x1000
	s_addc_u32 s9, s9, 0
; DEV void p5_pre(const Params& P, int p) {
;     ...
;     for (int pp = pfirst; pp < p; ++pp) {
;       const f32x2_t a2 = *(const f32x2_t*)(aprod + pp * DM + ch), h2 = *(const f32x2_t*)(hend + pp * DM + ch);
;       Ha = a2[0] * Ha + h2[0]; Hb = a2[1] * Hb + h2[1];
;     }
.Lpfx_wait:
	s_waitcnt vmcnt(0)
	s_cmp_le_u32 s6, 0
	s_cbranch_scc1 .Lpfx_done
	v_pk_fma_f32 v[6:7], v[6:7], v[8:9], v[10:11]
	s_cmp_le_u32 s6, 1
	s_cbranch_scc1 .Lpfx_done
	v_pk_fma_f32 v[6:7], v[6:7], v[12:13], v[14:15]
	s_cmp_le_u32 s6, 2
	s_cbranch_scc1 .Lpfx_done
	v_pk_fma_f32 v[6:7], v[6:7], v[16:17], v[18:19]
	s_cmp_le_u32 s6, 3
	s_cbranch_scc1 .Lpfx_done
	v_pk_fma_f32 v[6:7], v[6:7], v[20:21], v[22:23]
	s_cmp_le_u32 s6, 4
	s_cbranch_scc1 .Lpfx_done
	v_pk_fma_f32 v[6:7], v[6:7], v[24:25], v[26:27]
	s_cmp_le_u32 s6, 5
	s_cbranch_scc1 .Lpfx_done
	v_pk_fma_f32 v[6:7], v[6:7], v[28:29], v[30:31]
	s_cmp_le_u32 s6, 6
	s_cbranch_scc1 .Lpfx_done
	v_pk_fma_f32 v[6:7], v[6:7], v[32:33], v[34:35]
	s_cmp_le_u32 s6, 7
	s_cbranch_scc1 .Lpfx_done
	v_pk_fma_f32 v[6:7], v[6:7], v[36:37], v[38:39]
	s_cmp_le_u32 s6, 8
	s_cbranch_scc1 .Lpfx_done
	v_pk_fma_f32 v[6:7], v[6:7], v[40:41], v[42:43]
	s_cmp_le_u32 s6, 9
	s_cbranch_scc1 .Lpfx_done
	v_pk_fma_f32 v[6:7], v[6:7], v[44:45], v[46:47]
	s_cmp_le_u32 s6, 10
	s_cbranch_scc1 .Lpfx_done
	v_pk_fma_f32 v[6:7], v[6:7], v[48:49], v[50:51]
	s_cmp_le_u32 s6, 11
	s_cbranch_scc1 .Lpfx_done
	v_pk_fma_f32 v[6:7], v[6:7], v[52:53], v[54:55]
	s_cmp_le_u32 s6, 12
	s_cbranch_scc1 .Lpfx_done
	v_pk_fma_f32 v[6:7], v[6:7], v[56:57], v[58:59]
	s_cmp_le_u32 s6, 13
	s_cbranch_scc1 .Lpfx_done
	v_pk_fma_f32 v[6:7], v[6:7], v[60:61], v[62:63]
	s_cmp_le_u32 s6, 14
	s_cbranch_scc1 .Lpfx_done
	v_pk_fma_f32 v[6:7], v[6:7], v[64:65], v[66:67]
	s_cmp_le_u32 s6, 15
	s_cbranch_scc1 .Lpfx_done
	v_pk_fma_f32 v[6:7], v[6:7], v[68:69], v[70:71]
	s_cmp_le_u32 s6, 16
	s_cbranch_scc1 .Lpfx_done
	v_pk_fma_f32 v[6:7], v[6:7], v[72:73], v[74:75]
	s_cmp_le_u32 s6, 17
	s_cbranch_scc1 .Lpfx_done
	v_pk_fma_f32 v[6:7], v[6:7], v[76:77], v[78:79]
	s_cmp_le_u32 s6, 18
	s_cbranch_scc1 .Lpfx_done
	v_pk_fma_f32 v[6:7], v[6:7], v[80:81], v[82:83]
	s_cmp_le_u32 s6, 19
	s_cbranch_scc1 .Lpfx_done
	v_pk_fma_f32 v[6:7], v[6:7], v[84:85], v[86:87]
	s_cmp_le_u32 s6, 20
	s_cbranch_scc1 .Lpfx_done
	v_pk_fma_f32 v[6:7], v[6:7], v[88:89], v[90:91]
	s_cmp_le_u32 s6, 21
	s_cbranch_scc1 .Lpfx_done
	v_pk_fma_f32 v[6:7], v[6:7], v[92:93], v[94:95]
	s_cmp_le_u32 s6, 22
	s_cbranch_scc1 .Lpfx_done
	v_pk_fma_f32 v[6:7], v[6:7], v[96:97], v[98:99]
	s_cmp_le_u32 s6, 23
	s_cbranch_scc1 .Lpfx_done
	v_pk_fma_f32 v[6:7], v[6:7], v[100:101], v[102:103]
	s_sub_u32 s6, s6, 24
	s_cmp_lg_u32 s6, 0
	s_cbranch_scc1 .Lpfx_batch
.Lpfx_done:
.LBB0_705:
	s_mov_b64 s[0:1], 0
